# D unit: next-sequence tile loads and epilogue gate loads / mix stores use scalar bases + 32-bit lane offsets (no 64-bit VALU address arithmetic)
# speedup vs baseline: 1.0009x; 1.0009x over previous
; #define LAS __attribute__((address_space(3)))
; DI unsigned cvtpk(float lo, float hi) { f32x2_t v = {lo, hi}; bf16x2_t b = __builtin_convertvector(v, bf16x2_t); return __builtin_bit_cast(unsigned, b); }
; DI void unit_dilated2(int u, const bf16* __restrict__ Q, const bf16* __restrict__ K, const bf16* __restrict__ V, const bf16* __restrict__ G, bf16* __restrict__ MIX, LAS unsigned char* lds, int tid, int lane, int wave) {
;     ...
;     __syncthreads();
;     {   v4u gv[8], ov[8];
; #pragma unroll
;         for (int i = 0; i < 8; ++i) { const int id = tid + NT * i, row = id >> 3, c = id & 7;
;             gv[i] = *(const v4u*)(G + ((size_t)b * SEQ + T0 + row) * D + 256 + h * 64 + c * 8);
;             ov[i] = *(LAS const v4u*)(lds + DL_OBUF + row * 128 + ((c ^ ((row ^ (row >> 3) ^ (row >> 6)) & 7)) << 4)); }
; #pragma unroll
;         for (int i = 0; i < 8; ++i) { const int id = tid + NT * i, row = id >> 3, c = id & 7; v4u w;
; #pragma unroll
;             for (int e = 0; e < 4; ++e) w[e] = cvtpk(bflo(ov[i][e]) * bflo(gv[i][e]), bfhi(ov[i][e]) * bfhi(gv[i][e]));
;             *(v4u*)(MIX + ((size_t)b * SEQ + T0 + row) * D + 256 + h * 64 + c * 8) = w; }
;     }
.LBB0_745:
	v_ashrrev_i32_e32 v4, 3, v227
	s_lshl_b32 s38, s14, 1
	v_lshlrev_b32_e32 v5, 4, v227
	v_and_b32_e32 v44, 0x70, v5
	s_lshl_b64 s[0:1], s[10:11], 11
	s_add_u32 s0, s0, s38
	s_addc_u32 s1, s1, 0
	s_add_u32 s2, s24, s0
	s_addc_u32 s3, s25, s1
	s_add_u32 s0, s36, s0
	s_addc_u32 s1, s37, s1
	v_lshl_add_u32 v224, v4, 11, v44
	v_mov_b32_e32 v225, v224
	v_mov_b32_e32 v45, v2
	s_waitcnt lgkmcnt(0)
	s_barrier
	global_load_dwordx4 v[56:59], v224, s[2:3] offset:512
	v_add_u32_e32 v224, 0x20000, v224
	v_lshrrev_b32_e32 v6, 9, v227
	v_lshrrev_b32_e32 v3, 6, v227
	v_xor_b32_e32 v6, v227, v6
	v_xor_b32_e32 v6, v6, v3
	v_lshlrev_b32_e32 v5, 7, v4
	v_xor_b32_e32 v4, v6, v4
	v_lshlrev_b32_e32 v4, 4, v4
	v_and_b32_e32 v4, 0x70, v4
	v_add3_u32 v4, 0, v5, v4
	v_add_u32_e32 v8, 0x200, v227
	ds_read_b128 v[60:63], v4
	v_ashrrev_i32_e32 v4, 3, v8
	global_load_dwordx4 v[64:67], v224, s[2:3] offset:512
	v_add_u32_e32 v224, 0x20000, v224
	v_lshrrev_b32_e32 v6, 9, v8
	v_xor_b32_e32 v6, v227, v6
	v_xor_b32_e32 v6, v6, v3
	v_lshlrev_b32_e32 v5, 7, v4
	v_xor_b32_e32 v4, v6, v4
	v_lshlrev_b32_e32 v4, 4, v4
	v_and_b32_e32 v4, 0x70, v4
	v_add3_u32 v4, 0, v5, v4
	v_add_u32_e32 v8, 0x400, v227
	ds_read_b128 v[68:71], v4
	v_ashrrev_i32_e32 v4, 3, v8
	global_load_dwordx4 v[72:75], v224, s[2:3] offset:512
	v_add_u32_e32 v224, 0x20000, v224
	v_lshrrev_b32_e32 v6, 9, v8
	v_xor_b32_e32 v6, v227, v6
	v_xor_b32_e32 v6, v6, v3
	v_lshlrev_b32_e32 v5, 7, v4
	v_xor_b32_e32 v4, v6, v4
	v_lshlrev_b32_e32 v4, 4, v4
	v_and_b32_e32 v4, 0x70, v4
	v_add3_u32 v4, 0, v5, v4
	v_add_u32_e32 v8, 0x600, v227
	ds_read_b128 v[76:79], v4
	v_ashrrev_i32_e32 v4, 3, v8
	global_load_dwordx4 v[36:39], v224, s[2:3] offset:512
	v_add_u32_e32 v224, 0x20000, v224
	v_lshrrev_b32_e32 v6, 9, v8
	v_xor_b32_e32 v6, v227, v6
	v_xor_b32_e32 v6, v6, v3
	v_lshlrev_b32_e32 v5, 7, v4
	v_xor_b32_e32 v4, v6, v4
	v_lshlrev_b32_e32 v4, 4, v4
	v_and_b32_e32 v4, 0x70, v4
	v_add3_u32 v4, 0, v5, v4
	v_add_u32_e32 v8, 0x800, v227
	ds_read_b128 v[40:43], v4
	v_ashrrev_i32_e32 v4, 3, v8
	global_load_dwordx4 v[28:31], v224, s[2:3] offset:512
	v_add_u32_e32 v224, 0x20000, v224
	v_lshrrev_b32_e32 v6, 9, v8
	v_xor_b32_e32 v6, v227, v6
	v_xor_b32_e32 v6, v6, v3
	v_lshlrev_b32_e32 v5, 7, v4
	v_xor_b32_e32 v4, v6, v4
	v_lshlrev_b32_e32 v4, 4, v4
	v_and_b32_e32 v4, 0x70, v4
	v_add3_u32 v4, 0, v5, v4
	v_add_u32_e32 v8, 0xa00, v227
	ds_read_b128 v[32:35], v4
	v_ashrrev_i32_e32 v4, 3, v8
	global_load_dwordx4 v[20:23], v224, s[2:3] offset:512
	v_add_u32_e32 v224, 0x20000, v224
	v_lshrrev_b32_e32 v6, 9, v8
	v_xor_b32_e32 v6, v227, v6
	v_xor_b32_e32 v6, v6, v3
	v_lshlrev_b32_e32 v5, 7, v4
	v_xor_b32_e32 v4, v6, v4
	v_lshlrev_b32_e32 v4, 4, v4
	v_and_b32_e32 v4, 0x70, v4
	v_add3_u32 v4, 0, v5, v4
	v_add_u32_e32 v8, 0xc00, v227
	ds_read_b128 v[24:27], v4
	v_ashrrev_i32_e32 v4, 3, v8
	global_load_dwordx4 v[12:15], v224, s[2:3] offset:512
	v_add_u32_e32 v224, 0x20000, v224
	v_lshrrev_b32_e32 v6, 9, v8
	v_xor_b32_e32 v6, v227, v6
	v_xor_b32_e32 v6, v6, v3
	v_lshlrev_b32_e32 v5, 7, v4
	v_xor_b32_e32 v4, v6, v4
	v_lshlrev_b32_e32 v4, 4, v4
	v_add_u32_e32 v10, 0xe00, v227
	v_and_b32_e32 v4, 0x70, v4
	v_ashrrev_i32_e32 v8, 3, v10
	v_add3_u32 v4, 0, v5, v4
	ds_read_b128 v[16:19], v4
	global_load_dwordx4 v[4:7], v224, s[2:3] offset:512
	s_waitcnt lgkmcnt(6)
	v_lshlrev_b32_e32 v86, 16, v60
	v_and_b32_e32 v87, 0xffff0000, v60
	s_waitcnt vmcnt(7)
	v_lshlrev_b32_e32 v88, 16, v56
	v_and_b32_e32 v89, 0xffff0000, v56
	v_pk_mul_f32 v[86:87], v[88:89], v[86:87]
	v_lshlrev_b32_e32 v60, 16, v61
	v_cvt_pk_bf16_f32 v56, v86, v87
	v_and_b32_e32 v61, 0xffff0000, v61
	v_lshlrev_b32_e32 v86, 16, v57
	v_and_b32_e32 v87, 0xffff0000, v57
	v_pk_mul_f32 v[60:61], v[86:87], v[60:61]
	v_lshlrev_b32_e32 v86, 16, v58
	v_cvt_pk_bf16_f32 v57, v60, v61
	v_lshlrev_b32_e32 v60, 16, v62
	v_and_b32_e32 v61, 0xffff0000, v62
	v_and_b32_e32 v87, 0xffff0000, v58
	v_pk_mul_f32 v[60:61], v[86:87], v[60:61]
	v_lshlrev_b32_e32 v62, 16, v59
	v_cvt_pk_bf16_f32 v58, v60, v61
	v_lshlrev_b32_e32 v60, 16, v63
	v_and_b32_e32 v61, 0xffff0000, v63
	v_and_b32_e32 v63, 0xffff0000, v59
	v_pk_mul_f32 v[60:61], v[62:63], v[60:61]
	s_waitcnt vmcnt(6)
	v_lshlrev_b32_e32 v62, 16, v67
	v_cvt_pk_bf16_f32 v59, v60, v61
	global_store_dwordx4 v225, v[56:59], s[0:1] offset:512
	v_add_u32_e32 v225, 0x20000, v225
	v_lshlrev_b32_e32 v60, 16, v65
	v_and_b32_e32 v61, 0xffff0000, v65
	s_waitcnt lgkmcnt(5)
	v_lshlrev_b32_e32 v56, 16, v68
	v_and_b32_e32 v57, 0xffff0000, v68
	v_lshlrev_b32_e32 v58, 16, v64
	v_and_b32_e32 v59, 0xffff0000, v64
	v_pk_mul_f32 v[56:57], v[58:59], v[56:57]
	v_lshlrev_b32_e32 v58, 16, v69
	v_and_b32_e32 v59, 0xffff0000, v69
	v_pk_mul_f32 v[58:59], v[60:61], v[58:59]
	v_cvt_pk_bf16_f32 v56, v56, v57
	v_cvt_pk_bf16_f32 v57, v58, v59
	v_lshlrev_b32_e32 v58, 16, v70
	v_and_b32_e32 v59, 0xffff0000, v70
	v_lshlrev_b32_e32 v60, 16, v66
	v_and_b32_e32 v61, 0xffff0000, v66
	v_pk_mul_f32 v[58:59], v[60:61], v[58:59]
	v_lshlrev_b32_e32 v60, 16, v71
	v_and_b32_e32 v61, 0xffff0000, v71
	v_and_b32_e32 v63, 0xffff0000, v67
	v_pk_mul_f32 v[60:61], v[62:63], v[60:61]
	v_cvt_pk_bf16_f32 v58, v58, v59
	v_cvt_pk_bf16_f32 v59, v60, v61
	global_store_dwordx4 v225, v[56:59], s[0:1] offset:512
	v_add_u32_e32 v225, 0x20000, v225
	s_waitcnt vmcnt(7)
	v_lshlrev_b32_e32 v60, 16, v73
	v_and_b32_e32 v61, 0xffff0000, v73
	s_waitcnt lgkmcnt(4)
; DI unsigned cvtpk(float lo, float hi) { f32x2_t v = {lo, hi}; bf16x2_t b = __builtin_convertvector(v, bf16x2_t); return __builtin_bit_cast(unsigned, b); }
; DI void unit_dilated2(int u, const bf16* __restrict__ Q, const bf16* __restrict__ K, const bf16* __restrict__ V, const bf16* __restrict__ G, bf16* __restrict__ MIX, LAS unsigned char* lds, int tid, int lane, int wave) {
;     ...
; #pragma unroll
;         for (int i = 0; i < 8; ++i) { const int id = tid + NT * i, row = id >> 3, c = id & 7; v4u w;
; #pragma unroll
;             for (int e = 0; e < 4; ++e) w[e] = cvtpk(bflo(ov[i][e]) * bflo(gv[i][e]), bfhi(ov[i][e]) * bfhi(gv[i][e]));
;             *(v4u*)(MIX + ((size_t)b * SEQ + T0 + row) * D + 256 + h * 64 + c * 8) = w; }
	v_lshlrev_b32_e32 v56, 16, v76
	v_and_b32_e32 v57, 0xffff0000, v76
	v_lshlrev_b32_e32 v58, 16, v72
	v_and_b32_e32 v59, 0xffff0000, v72
	v_pk_mul_f32 v[56:57], v[58:59], v[56:57]
	v_lshlrev_b32_e32 v58, 16, v77
	v_and_b32_e32 v59, 0xffff0000, v77
	v_pk_mul_f32 v[58:59], v[60:61], v[58:59]
	v_cvt_pk_bf16_f32 v56, v56, v57
	v_cvt_pk_bf16_f32 v57, v58, v59
	v_lshlrev_b32_e32 v58, 16, v78
	v_and_b32_e32 v59, 0xffff0000, v78
	v_lshlrev_b32_e32 v60, 16, v74
	v_and_b32_e32 v61, 0xffff0000, v74
	v_pk_mul_f32 v[58:59], v[60:61], v[58:59]
	v_lshlrev_b32_e32 v60, 16, v79
	v_and_b32_e32 v61, 0xffff0000, v79
	v_lshlrev_b32_e32 v62, 16, v75
	v_and_b32_e32 v63, 0xffff0000, v75
	v_pk_mul_f32 v[60:61], v[62:63], v[60:61]
	v_cvt_pk_bf16_f32 v58, v58, v59
	v_cvt_pk_bf16_f32 v59, v60, v61
	global_store_dwordx4 v225, v[56:59], s[0:1] offset:512
	v_add_u32_e32 v225, 0x20000, v225
	v_lshrrev_b32_e32 v10, 9, v10
	v_xor_b32_e32 v10, v227, v10
	s_waitcnt lgkmcnt(3)
	v_lshlrev_b32_e32 v56, 16, v40
	v_and_b32_e32 v57, 0xffff0000, v40
	s_waitcnt vmcnt(7)
	v_lshlrev_b32_e32 v58, 16, v36
	v_and_b32_e32 v59, 0xffff0000, v36
	v_pk_mul_f32 v[56:57], v[58:59], v[56:57]
	v_lshlrev_b32_e32 v40, 16, v41
	v_cvt_pk_bf16_f32 v36, v56, v57
	v_and_b32_e32 v41, 0xffff0000, v41
	v_lshlrev_b32_e32 v56, 16, v37
	v_and_b32_e32 v57, 0xffff0000, v37
	v_pk_mul_f32 v[40:41], v[56:57], v[40:41]
	v_lshlrev_b32_e32 v56, 16, v38
	v_cvt_pk_bf16_f32 v37, v40, v41
	v_lshlrev_b32_e32 v40, 16, v42
	v_and_b32_e32 v41, 0xffff0000, v42
	v_and_b32_e32 v57, 0xffff0000, v38
	v_pk_mul_f32 v[40:41], v[56:57], v[40:41]
	v_lshlrev_b32_e32 v42, 16, v39
	v_cvt_pk_bf16_f32 v38, v40, v41
	v_lshlrev_b32_e32 v40, 16, v43
	v_and_b32_e32 v41, 0xffff0000, v43
	v_and_b32_e32 v43, 0xffff0000, v39
	v_pk_mul_f32 v[40:41], v[42:43], v[40:41]
	v_xor_b32_e32 v3, v10, v3
	v_cvt_pk_bf16_f32 v39, v40, v41
	global_store_dwordx4 v225, v[36:39], s[0:1] offset:512
	v_add_u32_e32 v225, 0x20000, v225
	v_xor_b32_e32 v3, v3, v8
	v_lshlrev_b32_e32 v3, 4, v3
	s_waitcnt lgkmcnt(2)
	v_lshlrev_b32_e32 v36, 16, v32
	v_and_b32_e32 v37, 0xffff0000, v32
	s_waitcnt vmcnt(7)
	v_lshlrev_b32_e32 v38, 16, v28
	v_and_b32_e32 v39, 0xffff0000, v28
	v_pk_mul_f32 v[36:37], v[38:39], v[36:37]
	v_lshlrev_b32_e32 v32, 16, v33
	v_cvt_pk_bf16_f32 v28, v36, v37
	v_and_b32_e32 v33, 0xffff0000, v33
	v_lshlrev_b32_e32 v36, 16, v29
	v_and_b32_e32 v37, 0xffff0000, v29
	v_pk_mul_f32 v[32:33], v[36:37], v[32:33]
	v_lshlrev_b32_e32 v36, 16, v30
	v_cvt_pk_bf16_f32 v29, v32, v33
	v_lshlrev_b32_e32 v32, 16, v34
	v_and_b32_e32 v33, 0xffff0000, v34
	v_and_b32_e32 v37, 0xffff0000, v30
	v_pk_mul_f32 v[32:33], v[36:37], v[32:33]
	v_lshlrev_b32_e32 v34, 16, v31
	v_cvt_pk_bf16_f32 v30, v32, v33
	v_lshlrev_b32_e32 v32, 16, v35
	v_and_b32_e32 v33, 0xffff0000, v35
	v_and_b32_e32 v35, 0xffff0000, v31
	v_pk_mul_f32 v[32:33], v[34:35], v[32:33]
	v_lshlrev_b32_e32 v9, 7, v8
	v_cvt_pk_bf16_f32 v31, v32, v33
	global_store_dwordx4 v225, v[28:31], s[0:1] offset:512
	v_add_u32_e32 v225, 0x20000, v225
	v_and_b32_e32 v3, 0x70, v3
	v_add3_u32 v3, 0, v9, v3
	s_waitcnt lgkmcnt(1)
	v_lshlrev_b32_e32 v28, 16, v24
	v_and_b32_e32 v29, 0xffff0000, v24
	s_waitcnt vmcnt(7)
	v_lshlrev_b32_e32 v30, 16, v20
	v_and_b32_e32 v31, 0xffff0000, v20
	v_pk_mul_f32 v[28:29], v[30:31], v[28:29]
	v_lshlrev_b32_e32 v24, 16, v25
	v_cvt_pk_bf16_f32 v20, v28, v29
	v_and_b32_e32 v25, 0xffff0000, v25
	v_lshlrev_b32_e32 v28, 16, v21
	v_and_b32_e32 v29, 0xffff0000, v21
	v_pk_mul_f32 v[24:25], v[28:29], v[24:25]
	v_lshlrev_b32_e32 v28, 16, v22
	v_cvt_pk_bf16_f32 v21, v24, v25
	v_lshlrev_b32_e32 v24, 16, v26
	v_and_b32_e32 v25, 0xffff0000, v26
	v_and_b32_e32 v29, 0xffff0000, v22
	v_pk_mul_f32 v[24:25], v[28:29], v[24:25]
	v_lshlrev_b32_e32 v26, 16, v23
	v_cvt_pk_bf16_f32 v22, v24, v25
	v_lshlrev_b32_e32 v24, 16, v27
	v_and_b32_e32 v25, 0xffff0000, v27
	v_and_b32_e32 v27, 0xffff0000, v23
	v_pk_mul_f32 v[24:25], v[26:27], v[24:25]
	ds_read_b128 v[8:11], v3
	v_cvt_pk_bf16_f32 v23, v24, v25
	global_store_dwordx4 v225, v[20:23], s[0:1] offset:512
	v_add_u32_e32 v225, 0x20000, v225
	s_waitcnt lgkmcnt(1)
	s_nop 0
	v_lshlrev_b32_e32 v20, 16, v16
	v_and_b32_e32 v21, 0xffff0000, v16
	s_waitcnt vmcnt(7)
	v_lshlrev_b32_e32 v22, 16, v12
	v_and_b32_e32 v23, 0xffff0000, v12
	v_pk_mul_f32 v[20:21], v[22:23], v[20:21]
	v_lshlrev_b32_e32 v16, 16, v17
	v_cvt_pk_bf16_f32 v12, v20, v21
	v_and_b32_e32 v17, 0xffff0000, v17
	v_lshlrev_b32_e32 v20, 16, v13
	v_and_b32_e32 v21, 0xffff0000, v13
	v_pk_mul_f32 v[16:17], v[20:21], v[16:17]
	v_lshlrev_b32_e32 v20, 16, v14
	v_cvt_pk_bf16_f32 v13, v16, v17
	v_lshlrev_b32_e32 v16, 16, v18
	v_and_b32_e32 v17, 0xffff0000, v18
	v_and_b32_e32 v21, 0xffff0000, v14
	v_pk_mul_f32 v[16:17], v[20:21], v[16:17]
	v_lshlrev_b32_e32 v18, 16, v15
	v_cvt_pk_bf16_f32 v14, v16, v17
	v_lshlrev_b32_e32 v16, 16, v19
	v_and_b32_e32 v17, 0xffff0000, v19
	v_and_b32_e32 v19, 0xffff0000, v15
	v_pk_mul_f32 v[16:17], v[18:19], v[16:17]
	s_nop 0
	v_cvt_pk_bf16_f32 v15, v16, v17
	global_store_dwordx4 v225, v[12:15], s[0:1] offset:512
	v_add_u32_e32 v225, 0x20000, v225
	s_waitcnt lgkmcnt(0)
	s_nop 0
	v_lshlrev_b32_e32 v12, 16, v8
	v_and_b32_e32 v13, 0xffff0000, v8
	s_waitcnt vmcnt(7)
	v_lshlrev_b32_e32 v14, 16, v4
	v_and_b32_e32 v15, 0xffff0000, v4
	v_pk_mul_f32 v[12:13], v[14:15], v[12:13]
	v_lshlrev_b32_e32 v8, 16, v9
	v_cvt_pk_bf16_f32 v4, v12, v13
	v_and_b32_e32 v9, 0xffff0000, v9
	v_lshlrev_b32_e32 v12, 16, v5
	v_and_b32_e32 v13, 0xffff0000, v5
	v_pk_mul_f32 v[8:9], v[12:13], v[8:9]
	v_lshlrev_b32_e32 v12, 16, v6
	v_cvt_pk_bf16_f32 v5, v8, v9
	v_lshlrev_b32_e32 v8, 16, v10
	v_and_b32_e32 v9, 0xffff0000, v10
	v_and_b32_e32 v13, 0xffff0000, v6
	v_pk_mul_f32 v[8:9], v[12:13], v[8:9]
	v_lshlrev_b32_e32 v10, 16, v7
	v_cvt_pk_bf16_f32 v6, v8, v9
	v_lshlrev_b32_e32 v8, 16, v11
	v_and_b32_e32 v9, 0xffff0000, v11
	v_and_b32_e32 v11, 0xffff0000, v7
	v_pk_mul_f32 v[8:9], v[10:11], v[8:9]
	s_nop 0
	v_cvt_pk_bf16_f32 v7, v8, v9
	global_store_dwordx4 v225, v[4:7], s[0:1] offset:512

; DI void unit_dilated2(int u, const bf16* __restrict__ Q, const bf16* __restrict__ K, const bf16* __restrict__ V, const bf16* __restrict__ G, bf16* __restrict__ MIX, LAS unsigned char* lds, int tid, int lane, int wave) {
;     ...
;     for (int seq = 0; seq < 6; ++seq) {
;         const DilWT nw = dil_wt(seq < 5 ? seq + 1 : 5, wave, b, h, T0, qq, slope2);
;         bf16x8 qn[4];
; #pragma unroll
;         for (int st = 0; st < 4; ++st) qn[st] = *(const bf16x8*)(Q + nw.qrow * 512 + h * 64 + 16 * st + 8 * hh);
;         f32x16 o0, o1;
; #pragma unroll
;         for (int i = 0; i < 16; ++i) { o0[i] = 0.f; o1[i] = 0.f; }
;         float m = NEG, l = 0.f;
; #pragma unroll 1
;         for (int a = 4; a >= cw.a0; --a) {
;             dil_store(kst, vst, kr, vr, lane);
;             if (a > cw.a0) dil_load(kr, vr, K, V, cw.rb0 + (long)(32 * (a - 1)) * cw.gstride, cw.gstride, lane);
;             else if (seq < 5) dil_load(kr, vr, K, V, nw.rb0 + (long)(32 * 4) * nw.gstride, nw.gstride, lane);
.LBB0_755:
	s_mov_b32 s35, s44
	s_add_i32 s44, s44, 1
	s_cmp_lg_u32 s35, 5
	s_cselect_b64 s[22:23], -1, 0
	s_and_b64 s[0:1], s[22:23], exec
	s_cselect_b32 s0, s44, 5
	s_lshl_b32 s1, s0, 3
	s_and_b32 s1, s1, 8
	s_and_b32 s0, s0, 14
	s_add_i32 s1, s1, s33
	s_sub_i32 s8, 4, s0
	s_mov_b64 s[2:3], s[16:17]
	s_lshr_b32 s16, s1, s8
	s_lshr_b32 s8, 16, s0
	s_add_i32 s8, s8, -1
	s_and_b32 s1, s1, s8
	s_lshl_b32 s9, s1, 5
	v_or_b32_e32 v3, s9, v228
	v_lshlrev_b32_e32 v3, s0, v3
	v_mov_b32_e32 v241, v184
	v_add_u32_e32 v184, s16, v3
	v_ashrrev_i32_e32 v185, 31, v184
	v_lshl_add_u64 v[4:5], s[10:11], 0, v[184:185]
	v_lshlrev_b64 v[4:5], 10, v[4:5]
	s_waitcnt vmcnt(0)
	v_mov_b64_e32 v[164:165], v[132:133]
	v_mov_b64_e32 v[168:169], v[124:125]
	v_mov_b64_e32 v[172:173], v[120:121]
	v_mov_b64_e32 v[176:177], v[116:117]
	v_lshl_add_u64 v[4:5], v[196:197], 0, v[4:5]
	v_mov_b64_e32 v[162:163], v[130:131]
	v_mov_b64_e32 v[166:167], v[122:123]
	v_mov_b64_e32 v[170:171], v[118:119]
	v_mov_b64_e32 v[174:175], v[114:115]
	global_load_dwordx4 v[114:117], v[4:5], off
	global_load_dwordx4 v[118:121], v[4:5], off offset:32
	global_load_dwordx4 v[122:125], v[4:5], off offset:64
	global_load_dwordx4 v[130:133], v[4:5], off offset:96
	s_lshr_b32 s8, s34, s0
	s_add_i32 s1, s9, s8
	s_add_i32 s8, s1, 0xffffff80
	s_ashr_i32 s9, s8, 31
	s_lshl_b32 s38, 0x200, s0
	s_lshl_b64 s[8:9], s[8:9], s0
	s_add_u32 s16, s12, s16
	s_addc_u32 s17, s13, 0
	s_add_u32 s8, s16, s8
	s_addc_u32 s9, s17, s9
	s_lshl_b64 s[8:9], s[8:9], 9
	s_or_b64 s[16:17], s[8:9], s[14:15]
	s_mov_b64 s[20:21], s[18:19]
	s_mov_b64 s[18:19], s[38:39]
	s_lshl_b32 s38, s38, 7
	s_add_i32 s8, s0, 9
	s_sub_u32 s9, s80, s76
	v_lshlrev_b32_e32 v4, s8, v186
	v_lshlrev_b32_e32 v5, s8, v190
	v_lshlrev_b32_e32 v6, s8, v192
	v_lshlrev_b32_e32 v7, s8, v194
	v_add_lshl_u32 v200, v4, v188, 1
	v_add_lshl_u32 v201, v5, v188, 1
	v_add_lshl_u32 v202, v6, v188, 1
	v_add_lshl_u32 v203, v7, v188, 1
	v_add_u32_e32 v204, s9, v200
	v_add_u32_e32 v205, s9, v201
	v_add_u32_e32 v206, s9, v202
	v_add_u32_e32 v207, s9, v203
	v_mul_lo_u32 v216, s20, v186
	s_mul_i32 s8, s20, 0x60
	s_add_u32 s8, s2, s8
	s_addc_u32 s9, s3, 0
	s_lshl_b64 s[8:9], s[8:9], 1
	s_add_u32 s8, s8, s76
	s_addc_u32 s9, s9, s77
	s_sub_u32 s3, s80, s76
	s_lshl_b32 s2, s20, 4
	v_add_lshl_u32 v216, v216, v188, 1
	v_add_u32_e32 v217, s2, v216
	v_add_u32_e32 v218, s2, v217
	v_add_u32_e32 v219, s2, v218
	v_add_u32_e32 v220, s3, v216
	v_add_u32_e32 v221, s3, v217
	v_add_u32_e32 v222, s3, v218
	v_add_u32_e32 v223, s3, v219
	v_mul_f32_e32 v4, v199, v231
	v_mul_f32_e32 v198, 0, v199
	v_mov_b32_e32 v6, v199
	v_mov_b32_e32 v16, v2
	v_mov_b32_e32 v17, v2
	v_pk_add_f32 v[18:19], v[198:199], v[4:5] op_sel_hi:[1,0]
	v_pk_fma_f32 v[20:21], v[6:7], s[96:97], v[4:5] op_sel_hi:[0,1,0]
	v_pk_fma_f32 v[22:23], v[6:7], s[74:75], v[4:5] op_sel_hi:[0,1,0]
	v_pk_fma_f32 v[24:25], v[6:7], s[82:83], v[4:5] op_sel_hi:[0,1,0]
	v_pk_fma_f32 v[26:27], v[6:7], s[86:87], v[4:5] op_sel_hi:[0,1,0]
	v_pk_fma_f32 v[28:29], v[6:7], s[90:91], v[4:5] op_sel_hi:[0,1,0]
	v_pk_fma_f32 v[30:31], v[6:7], s[68:69], v[4:5] op_sel_hi:[0,1,0]
	v_pk_fma_f32 v[32:33], v[6:7], s[70:71], v[4:5] op_sel_hi:[0,1,0]
	s_lshl_b32 s2, s20, 6
	s_mov_b32 s31, 4
	s_mov_b32 s51, 0
	v_mov_b32_e32 v198, 0xf149f2ca
	v_mov_b32_e32 v185, 0

; DI void dil_load(v4u (&kr)[4], v4u (&vr)[4], const bf16* K, const bf16* V, long rowbase, long gstride, int lane) {
; #pragma unroll
;     for (int n = 0; n < 4; ++n) { const long off = rowbase + (long)((lane >> 3) + 8 * n) * gstride + (lane & 7) * 8; kr[n] = *(const v4u*)(K + off); vr[n] = *(const v4u*)(V + off); }
; }
; DI void unit_dilated2(int u, const bf16* __restrict__ Q, const bf16* __restrict__ K, const bf16* __restrict__ V, const bf16* __restrict__ G, bf16* __restrict__ MIX, LAS unsigned char* lds, int tid, int lane, int wave) {
;     ...
;             else if (seq < 5) dil_load(kr, vr, K, V, nw.rb0 + (long)(32 * 4) * nw.gstride, nw.gstride, lane);
.Ldil_ld_nextwt:
	s_andn2_b64 vcc, exec, s[22:23]
	s_cbranch_vccnz .Ldil_ld_done
	s_add_u32 s8, s16, s38
	s_addc_u32 s9, s17, 0
	s_lshl_b64 s[8:9], s[8:9], 1
	s_add_u32 s8, s8, s76
	s_addc_u32 s9, s9, s77
	global_load_dwordx4 v[126:129], v200, s[8:9]
	global_load_dwordx4 v[134:137], v204, s[8:9]
	global_load_dwordx4 v[138:141], v201, s[8:9]
	global_load_dwordx4 v[142:145], v205, s[8:9]
	global_load_dwordx4 v[146:149], v202, s[8:9]
	global_load_dwordx4 v[150:153], v206, s[8:9]
	global_load_dwordx4 v[154:157], v203, s[8:9]
	global_load_dwordx4 v[158:161], v207, s[8:9]
